# static priority raise (s_setprio 1) for waves 0-3 during the HGRN scan and the MLA tile loops
# speedup vs baseline: 1.0053x; 1.0048x over previous
; __device__ __forceinline__ int otid() { int t = threadIdx.x; asm volatile("" : "+v"(t)); return t; }
; template <bool DRY> __device__ __forceinline__ void hgrn_unit(LAS unsigned char* lds, int b, int h, int vs, int layer, bf16_t* Pm, const float* lbraw) {
;     using namespace hg;
;     const int tid = otid(), lane = tid & 63; const int wid = __builtin_amdgcn_readfirstlane(tid >> 6);
;     const size_t tok0 = (size_t)b * SEQ;
;     const int kl = lane & 15, tq = lane >> 4, kch = 16 * wid + kl;
;     (void)layer; (void)lbraw;
;     const bf16_t* qsrc = Pm + (tok0 + 4 * tq) * PW + PC_HQ + h * 128 + (kch & ~1);
;     const bf16_t* fsrc = Pm + (tok0 + 4 * tq) * PW + PC_HF + h * 128 + (kch & ~1);
;     const bool isv = tid < 128; const int vv = tid & 31, vtq = (tid >> 5) & 3;
.LBB0_615:
	s_or_b64 exec, exec, s[6:7]
	s_ashr_i32 s6, s22, 4
	s_ashr_i32 s7, s6, 31
	v_bfe_u32 v9, v3, 4, 2
	s_lshl_b64 s[14:15], s[6:7], 11
	v_lshlrev_b32_e32 v8, 2, v9
	v_or_b32_e32 v0, s14, v8
	v_mov_b64_e32 v[4:5], s[4:5]
	v_bfe_u32 v12, v3, 5, 2
	s_ashr_i32 s28, s10, 6
	s_mov_b32 s65, s28
	s_cmp_ge_u32 s65, 4
	s_cbranch_scc1 .Lprio_hg
	s_setprio 1

; __device__ __forceinline__ int otid() { int t = threadIdx.x; asm volatile("" : "+v"(t)); return t; }
; template <bool DRY> __device__ __forceinline__ void mla_unit(LAS unsigned char* lds, int b, int h, int qb, const bf16_t* Q, const bf16_t* Kn, const bf16_t* Pm, const bf16_t* VT, bf16_t* Y) {
;     const int tid = otid(), lane = tid & 63, r32 = lane & 31, hi = lane >> 5; const int wid = __builtin_amdgcn_readfirstlane(tid >> 6);
;     const int NT = 4 * qb + 4, tmax = 4 * qb + (wid >> 1);
;     const size_t tok0 = (size_t)b * SEQ;
;     const size_t qtok = tok0 + qb * 256 + wid * 32 + r32;
.LBB0_801:
	s_lshr_b32 s22, s55, 1
	s_or_b32 s22, s22, s53
	s_and_b32 s23, s55, 1
	s_sub_i32 s28, 7, s22
	v_mov_b32_e32 v3, v234
	s_cmp_eq_u32 s23, 0
	s_cselect_b32 s42, s22, s28
	v_readfirstlane_b32 s43, v3
	v_and_b32_e32 v14, 31, v3
	s_bitcmp1_b32 s43, 8
	s_cbranch_scc1 .Lprio_ml
	s_setprio 1
